# v60 + grid-barrier leaders poll the cross-XCD arrival counter directly (skip TOPGEN hop)
# speedup vs baseline: 1.0087x; 1.0003x over previous
.LBB0_137:
	s_or_b64 exec, exec, s[10:11]
	v_cvt_f32_u32_e32 v4, v1
	s_waitcnt vmcnt(0)
	v_readfirstlane_b32 s2, v3
	s_add_u32 s10, s78, 0xe813500
	s_addc_u32 s11, s79, 0
	v_rcp_iflag_f32_e32 v4, v4
	v_add_u32_e32 v2, s2, v2
	v_add_u32_e32 v5, 1, v2
	s_mov_b64 s[12:13], -1
	v_mul_f32_e32 v3, 0x4f7ffffe, v4
	v_cvt_u32_f32_e32 v3, v3
	v_sub_u32_e32 v4, 0, v1
	v_mul_lo_u32 v4, v4, v3
	v_mul_hi_u32 v4, v3, v4
	v_add_u32_e32 v3, v3, v4
	v_mul_hi_u32 v3, v2, v3
	v_mul_lo_u32 v4, v3, v1
	v_sub_u32_e32 v2, v2, v4
	v_add_u32_e32 v6, 1, v3
	v_cmp_ge_u32_e32 vcc, v2, v1
	v_sub_u32_e32 v4, v2, v1
	s_nop 0
	v_cndmask_b32_e32 v3, v3, v6, vcc
	v_cndmask_b32_e32 v2, v2, v4, vcc
	v_add_u32_e32 v4, 1, v3
	v_cmp_ge_u32_e32 vcc, v2, v1
	s_nop 1
	v_cndmask_b32_e32 v4, v3, v4, vcc
	v_mul_lo_u32 v2, v1, v4
	v_add_u32_e32 v1, v2, v1
	v_mov_b32_e32 v6, v1
	v_mov_b32_e32 v7, 0xe813000
	s_nop 0
	v_cmp_ne_u32_e32 vcc, v5, v1
	v_mov_b64_e32 v[2:3], s[10:11]
	s_and_saveexec_b64 s[8:9], vcc
	s_cbranch_execz .LBB0_149
	v_mov_b32_e32 v1, 0
	global_load_dword v2, v7, s[78:79] offset:1024 sc1
	s_mov_b64 s[16:17], 0
	s_waitcnt vmcnt(0)
	v_cmp_lt_u32_e32 vcc, v2, v6
	s_and_saveexec_b64 s[14:15], vcc
	s_cbranch_execz .LBB0_148
	s_add_u32 s12, s78, 0xe810200
	s_addc_u32 s13, s79, 0
	s_mov_b32 s2, 1
	s_branch .LBB0_141

.LBB0_143:
	global_load_dword v2, v7, s[78:79] offset:1024 sc1
	s_add_i32 s2, s2, 1
	s_mov_b64 s[18:19], -1
	s_waitcnt vmcnt(0)
	v_cmp_ge_u32_e32 vcc, v2, v6
	s_orn2_b64 s[24:25], vcc, exec
	s_branch .LBB0_140
